# resume: re-measure v163 after container loss
# baseline (speedup 1.0000x reference)
.LBB0_343:
	s_nop 0
	s_nop 0
	s_barrier
	s_and_saveexec_b64 s[0:1], s[4:5]
	v_readlane_b32 s31, v244, 17
	v_readlane_b32 s34, v244, 18
	v_readlane_b32 s35, v244, 19
	v_readlane_b32 s88, v244, 20
	v_readlane_b32 s89, v244, 21
	s_cbranch_execz .LBB0_354
	s_mov_b64 s[2:3], exec
	v_mbcnt_lo_u32_b32 v0, s2, 0
	v_mbcnt_hi_u32_b32 v0, s3, v0
	v_cmp_eq_u32_e32 vcc, 0, v0
	buffer_wbl2 sc1
	s_waitcnt vmcnt(0)
	s_and_saveexec_b64 s[6:7], vcc
	s_cbranch_execz .LBB0_346
	s_bcnt1_i32_b64 s2, s[2:3]
	v_mov_b32_e32 v1, s2
	v_readlane_b32 s2, v245, 43
	v_readlane_b32 s3, v245, 44
	s_nop 4
	global_atomic_add v1, v179, v1, s[2:3] offset:128 sc0
